# ffn-up and ffn-down fused: no grid barrier between them, new tile orders, per-row-block completion counters, write-through ffn-up stores
# speedup vs baseline: 1.0181x; 1.0181x over previous
; __device__ __forceinline__ float rsq(float x) { return __builtin_amdgcn_rsqf(x); }
;     __device__ bool next(int i, Unit& u) const {
;         const long L = (long)i * G + c; if (L >= nwg) return false;
; template <class EpiT, class Sched>
; __device__ __forceinline__ void gemm_phase(LAS unsigned char* lds, const Gemm g, const Sched& S, const EpiT& E, int wv) {
;     ...
;     Unit cur, nxt; int ui = 0;
;     if (!S.next(0, cur)) return;
;     if constexpr (EpiT::TAB) {
;         Unit tu;
;         for (int i = 0; S.next(i, tu); ++i) {
;             if (tid < 256) { const f32x4* pp = (const f32x4*)(E.partr + (size_t)(tu.pm * BM + tid) * 16); const f32x4 p0 = pp[0], p1 = pp[1], p2 = pp[2], p3 = pp[3];
;                 const f32x4 ps = (p0 + p1) + (p2 + p3); tab[i * 512 + tid] = rsq(((ps[0] + ps[1]) + (ps[2] + ps[3])) * (1.f / DM) + EPS); }
;             else { const int mr = (tu.pm * BM < MX) ? ((tu.pm * BM) >> 11) : 8; tab[i * 512 + tid] = E.bias[(size_t)mr * E.bias_ld + tu.pn * BM + (tid - 256)]; }
.LBB0_1254:
	s_or_b64 exec, exec, s[0:1]
	v_readlane_b32 s2, v255, 0
	v_readlane_b32 s3, v255, 1
	s_mov_b32 s0, s79
	s_waitcnt lgkmcnt(0)
	s_barrier
	v_mbcnt_lo_u32_b32 v8, -1, 0
	v_mbcnt_hi_u32_b32 v8, -1, v8
	s_movk_i32 s5, 0x400
	s_cmp_eq_u32 s90, 3
	s_cselect_b32 s4, 0, 32
	s_cselect_b32 s5, 0x300, s5
	s_cmp_lt_u32 s79, s4
	s_cselect_b32 s5, 0, s5
	s_add_i32 s36, s79, 1
	s_add_i32 s36, s36, s5
	s_mov_b32 s37, 0
	s_cmp_lt_i32 s0, s36
	v_or_b32_e32 v192, s67, v8
	s_nop 0
	v_readfirstlane_b32 s12, v192
	s_cbranch_scc0 .LBB0_1278
	s_load_dwordx2 s[6:7], s[2:3], 0xd8
	s_movk_i32 s1, 0xff
	v_cmp_lt_i32_e64 s[2:3], s1, v192
	v_readlane_b32 s8, v255, 22
	s_waitcnt lgkmcnt(0)
	s_add_u32 s4, s6, 0x1fa00000
	s_addc_u32 s5, s7, 0
	s_ashr_i32 s1, s0, 31
	v_lshl_add_u32 v0, v192, 2, s8
	s_mov_b64 s[8:9], s[0:1]
	s_branch .LBB0_1258

; __device__ __forceinline__ float rsq(float x) { return __builtin_amdgcn_rsqf(x); }
;     __device__ bool next(int i, Unit& u) const {
;         const long L = (long)i * G + c; if (L >= nwg) return false;
;         int wgid = (int)L; { const int q = nwg / NXCD, r = nwg % NXCD, xcd = wgid % NXCD, off = wgid / NXCD; wgid = (xcd < r ? xcd * (q + 1) : r * (q + 1) + (xcd - r) * q) + off; }
;         const int nig = WGM * nN, gid = wgid / nig, fm = gid * WGM, gsz = (nM - fm) < WGM ? (nM - fm) : WGM;
;         u.pm = fm + ((wgid % nig) % gsz); u.pn = (wgid % nig) / gsz; return true;
; template <class EpiT, class Sched>
; __device__ __forceinline__ void gemm_phase(LAS unsigned char* lds, const Gemm g, const Sched& S, const EpiT& E, int wv) {
;     ...
;         for (int i = 0; S.next(i, tu); ++i) {
;             if (tid < 256) { const f32x4* pp = (const f32x4*)(E.partr + (size_t)(tu.pm * BM + tid) * 16); const f32x4 p0 = pp[0], p1 = pp[1], p2 = pp[2], p3 = pp[3];
;                 const f32x4 ps = (p0 + p1) + (p2 + p3); tab[i * 512 + tid] = rsq(((ps[0] + ps[1]) + (ps[2] + ps[3])) * (1.f / DM) + EPS); }
;             else { const int mr = (tu.pm * BM < MX) ? ((tu.pm * BM) >> 11) : 8; tab[i * 512 + tid] = E.bias[(size_t)mr * E.bias_ld + tu.pn * BM + (tid - 256)]; }
.LBB0_1258:
	v_mov_b64_e32 v[2:3], s[36:37]
	v_cmp_ge_i64_e32 vcc, s[8:9], v[2:3]
	s_mov_b64 s[10:11], -1
	s_cbranch_vccnz .LBB0_1257
	s_ashr_i32 s10, s8, 31
	s_lshr_b32 s10, s10, 29
	s_add_i32 s10, s8, s10
	s_ashr_i32 s11, s10, 3
	s_and_b32 s10, s10, -8
	s_sub_i32 s10, s8, s10
	s_cmp_lt_i32 s10, 0
	s_cselect_b32 s13, s44, s43
	s_mul_i32 s10, s13, s10
	s_add_i32 s10, s10, s11
	s_ashr_i32 s11, s10, 31
	s_lshr_b32 s11, s11, 25
	s_add_i32 s11, s10, s11
	s_ashr_i32 s13, s11, 7
	s_lshl_b32 s13, s13, 3
	s_sub_i32 s14, s42, s13
	s_min_i32 s15, s14, 8
	s_abs_i32 s14, s15
	v_cvt_f32_u32_e32 v1, s14
	s_sub_i32 s17, 0, s14
	s_and_b32 s11, s11, 0xffffff80
	s_sub_i32 s10, s10, s11
	v_rcp_iflag_f32_e32 v1, v1
	s_abs_i32 s11, s10
	s_xor_b32 s16, s10, s15
	s_ashr_i32 s16, s16, 31
	v_mul_f32_e32 v1, 0x4f7ffffe, v1
	v_cvt_u32_f32_e32 v1, v1
	s_nop 0
	v_readfirstlane_b32 s18, v1
	s_mul_i32 s17, s17, s18
	s_mul_hi_u32 s17, s18, s17
	s_add_i32 s18, s18, s17
	s_mul_hi_u32 s17, s11, s18
	s_mul_i32 s18, s17, s14
	s_sub_i32 s11, s11, s18
	s_add_i32 s19, s17, 1
	s_sub_i32 s18, s11, s14
	s_cmp_ge_u32 s11, s14
	s_cselect_b32 s17, s19, s17
	s_cselect_b32 s11, s18, s11
	s_add_i32 s18, s17, 1
	s_cmp_ge_u32 s11, s14
	s_cselect_b32 s11, s18, s17
	s_xor_b32 s11, s11, s16
	s_sub_i32 s14, s11, s16
	s_mul_i32 s11, s14, s15
	s_sub_i32 s10, s10, s11
	s_add_i32 s13, s10, s13
	s_and_b32 s15, s8, 0xff
	s_lshr_b32 s16, s8, 8
	s_movk_i32 s17, 0xe0
	s_cmp_eq_u32 s90, 3
	s_cselect_b32 s17, 0x100, s17
	s_mul_i32 s17, s16, s17
	s_add_i32 s17, s15, s17
	s_lshr_b32 s13, s17, 4
	s_and_b32 s14, s17, 15
	s_and_saveexec_b64 s[10:11], s[2:3]
	s_xor_b64 s[10:11], exec, s[10:11]
	s_cbranch_execz .LBB0_1261
	s_min_i32 s15, s13, 64
	s_ashr_i32 s16, s15, 3
	s_ashr_i32 s17, s16, 31
	s_lshl_b32 s14, s14, 8
	s_ashr_i32 s15, s14, 31
	s_lshl_b64 s[16:17], s[16:17], 14
	s_add_u32 s16, s6, s16
	s_addc_u32 s17, s7, s17
	s_lshl_b64 s[14:15], s[14:15], 2
	s_add_u32 s14, s16, s14
	s_addc_u32 s15, s17, s15
	v_lshl_add_u64 v[2:3], v[192:193], 2, s[14:15]
	v_add_co_u32_e32 v2, vcc, 0x31cf000, v2
	s_nop 1
	v_addc_co_u32_e32 v3, vcc, 0, v3, vcc
	global_load_dword v1, v[2:3], off offset:3072

; #define otid() ((wv << 6) | olane())
; #define PG8_STAGE(bufoff, gbase, voff) do { _Pragma("unroll") for (int _i = 0; _i < 2; ++_i) \
;         __builtin_amdgcn_global_load_lds((const unsigned*)((const char*)(gbase) + (voff)[_i]), (LAS unsigned*)(lds + (bufoff) + ldsw + _i * 8192), 16, 0, 0); } while (0)
; #define PG8_WAIT_V(n) asm volatile("s_waitcnt vmcnt(" #n ")" ::: "memory")
; #define PG8_BAR __builtin_amdgcn_s_barrier()
; template <class EpiT, class Sched>
; __device__ __forceinline__ void gemm_phase(LAS unsigned char* lds, const Gemm g, const Sched& S, const EpiT& E, int wv) {
;     ...
;     const int tid = otid(), wid = __builtin_amdgcn_readfirstlane(tid >> 6), lane = tid & 63, wr = wid >> 2, wc = wid & 3, fr = lane & 15, fq = lane >> 4;
;     const int K = g.K, nt = K / BK;
;     unsigned voffA[2], voffB[2];
; #pragma unroll
;     for (int i = 0; i < 2; ++i) { int R, C; stage_rc(tid * 16 + i * 8192, R, C); const int Rb = EpiT::PERM ? ((R & ~31) + perm32(R & 31)) : R;
;         voffA[i] = (unsigned)(R * g.lda + C) * 2u; voffB[i] = (unsigned)(Rb * g.ldb + C) * 2u; }
;     const size_t kstep = (size_t)(BK * 2);
;     const size_t hstepA = (size_t)HALF * g.lda * 2, hstepB = (size_t)HALF * g.ldb * 2;
;     const size_t tstepA = 2 * hstepA, tstepB = 2 * hstepB;
;     const unsigned ldsw = (unsigned)wid * 1024u;
;     const int foff = lds_byte(fr, fq * 8);
;     const int aoff = wr * 8192 + foff, boff = wc * 4096 + foff;
;     ...
;     const char* cA = (const char*)g.A + (size_t)cur.pm * tstepA + (size_t)(cur.pn >> g.zshift) * g.zA; const char* cB = (const char*)g.Bt + (size_t)cur.pn * tstepB;
;     PG8_STAGE(PG8_SB(0, 0), cB, voffB); PG8_STAGE(PG8_SB(0, 1), cB + hstepB, voffB); PG8_STAGE(PG8_SA(0, 0), cA, voffA); PG8_STAGE(PG8_SA(0, 1), cA + hstepA, voffA);
;     if (wr == 1) PG8_BAR;
;     PG8_WAIT_V(2); PG8_BAR;
;     PG8_STAGE(PG8_SB(1, 0), cB + kstep, voffB); PG8_STAGE(PG8_SA(1, 0), cA + kstep, voffA); PG8_STAGE(PG8_SB(1, 1), cB + hstepB + kstep, voffB);
;     PG8_WAIT_V(6); PG8_BAR;
.LBB0_1263:
	s_ashr_i32 s2, s0, 31
	s_lshr_b32 s2, s2, 29
	s_add_i32 s2, s0, s2
	s_ashr_i32 s3, s2, 3
	s_and_b32 s2, s2, -8
	s_sub_i32 s2, s0, s2
	s_cmp_lt_i32 s2, 0
	s_cselect_b32 s4, s44, s43
	s_mul_i32 s2, s2, s4
	s_add_i32 s2, s2, s3
	s_ashr_i32 s3, s2, 31
	s_lshr_b32 s3, s3, 25
	s_add_i32 s3, s2, s3
	s_ashr_i32 s4, s3, 7
	s_lshl_b32 s4, s4, 3
	s_sub_i32 s5, s42, s4
	s_min_i32 s5, s5, 8
	s_abs_i32 s8, s5
	v_cvt_f32_u32_e32 v0, s8
	s_sub_i32 s10, 0, s8
	v_ashrrev_i32_e32 v1, 31, v192
	s_and_b32 s3, s3, 0xffffff80
	v_rcp_iflag_f32_e32 v0, v0
	v_lshrrev_b32_e32 v1, 26, v1
	s_sub_i32 s2, s2, s3
	v_add_u32_e32 v1, v192, v1
	v_mul_f32_e32 v0, 0x4f7ffffe, v0
	v_cvt_u32_f32_e32 v0, v0
	s_abs_i32 s3, s2
	v_ashrrev_i32_e32 v9, 6, v1
	v_bfe_i32 v1, v192, 27, 1
	v_readfirstlane_b32 s11, v0
	s_mul_i32 s10, s10, s11
	s_mul_hi_u32 s10, s11, s10
	s_add_i32 s11, s11, s10
	s_mul_hi_u32 s10, s3, s11
	v_lshlrev_b32_e32 v0, 4, v192
	v_lshrrev_b32_e32 v1, 22, v1
	s_mul_i32 s11, s10, s8
	v_add_u32_e32 v1, v0, v1
	s_xor_b32 s9, s2, s5
	s_sub_i32 s3, s3, s11
	v_and_b32_e32 v1, 0xfffffc00, v1
	s_ashr_i32 s9, s9, 31
	s_add_i32 s13, s10, 1
	s_sub_i32 s11, s3, s8
	v_sub_u32_e32 v1, v0, v1
	s_cmp_ge_u32 s3, s8
	v_lshrrev_b32_e32 v2, 4, v1
	s_cselect_b32 s10, s13, s10
	v_bitop3_b32 v1, v2, v1, 32 bitop3:0x6c
	s_cselect_b32 s3, s11, s3
	s_add_i32 s11, s10, 1
	v_ashrrev_i32_e32 v3, 31, v1
	s_cmp_ge_u32 s3, s8
	v_lshrrev_b32_e32 v3, 26, v3
	s_cselect_b32 s3, s11, s10
	v_add_u32_e32 v3, v1, v3
	s_xor_b32 s3, s3, s9
	v_lshlrev_b32_e32 v2, 3, v9
	v_ashrrev_i32_e32 v10, 6, v3
	v_and_b32_e32 v3, 0xc0, v3
	s_sub_i32 s18, s3, s9
	v_and_b32_e32 v2, -16, v2
	v_sub_u32_e32 v1, v1, v3
	s_mul_i32 s3, s18, s5
	v_add_u32_e32 v2, v10, v2
	v_ashrrev_i16_sdwa v1, v224, sext(v1) dst_sel:DWORD dst_unused:UNUSED_PAD src0_sel:DWORD src1_sel:BYTE_0
	s_sub_i32 s2, s2, s3
	v_lshlrev_b32_e32 v4, 5, v9
	v_bfe_i32 v11, v1, 0, 16
	v_lshlrev_b32_e32 v1, 1, v2
	v_lshrrev_b32_e32 v3, 2, v2
	v_and_b32_e32 v5, 3, v10
	s_mov_b32 s3, 0x1fffe0
	v_and_b32_e32 v4, 32, v4
	v_and_b32_e32 v1, 24, v1
	v_and_b32_e32 v3, 4, v3
	v_and_or_b32 v5, v2, s3, v5
	v_or3_b32 v1, v5, v3, v1
	v_add_lshl_u32 v3, v4, v11, 1
	v_add_u32_e32 v0, 0x2000, v0
	v_lshl_add_u32 v192, v1, 11, v3
	v_ashrrev_i32_e32 v1, 31, v0
	v_lshrrev_b32_e32 v1, 22, v1
	v_add_u32_e32 v1, v0, v1
	v_ashrrev_i32_e32 v12, 10, v1
	v_mul_i32_i24_e32 v1, 0x400, v12
	v_sub_u32_e32 v0, v0, v1
	v_lshrrev_b32_e32 v1, 4, v0
	v_bitop3_b32 v0, v1, v0, 32 bitop3:0x6c
	s_add_i32 s20, s4, s2
	s_lshr_b32 s20, s79, 4
	s_and_b32 s18, s79, 15
	v_lshl_add_u32 v136, v2, 11, v3
	v_ashrrev_i32_e32 v2, 31, v0
	s_add_u32 s28, s6, 0x3c00000
	v_lshrrev_b32_e32 v2, 26, v2
	s_addc_u32 s29, s7, 0
	v_lshlrev_b32_e32 v1, 3, v12
	v_add_u32_e32 v2, v0, v2
	s_add_u32 s30, s6, 0x1f00000
	v_and_b32_e32 v1, -16, v1
	v_ashrrev_i32_e32 v13, 6, v2
	s_addc_u32 s31, s7, 0
	s_ashr_i32 s2, s12, 6
	v_add_u32_e32 v1, v13, v1
	v_and_b32_e32 v2, 0xc0, v2
	v_and_b32_e32 v4, 3, v13
	s_ashr_i32 s21, s20, 31
	s_ashr_i32 s19, s18, 31
	v_sub_u32_e32 v0, v0, v2
	v_and_or_b32 v4, v1, s3, v4
	s_ashr_i32 s3, s12, 8
	s_lshl_b32 s33, s2, 10
	s_lshl_b64 s[4:5], s[20:21], 19
	s_lshl_b64 s[8:9], s[18:19], 19
	v_ashrrev_i16_sdwa v0, v224, sext(v0) dst_sel:DWORD dst_unused:UNUSED_PAD src0_sel:DWORD src1_sel:BYTE_0
	s_add_u32 s24, s30, s8
	v_lshlrev_b32_e32 v3, 5, v12
	v_bfe_i32 v14, v0, 0, 16
	v_lshlrev_b32_e32 v0, 1, v1
	v_lshrrev_b32_e32 v2, 2, v1
	s_addc_u32 s25, s31, s9
	s_add_i32 s19, s33, 0
	v_and_b32_e32 v3, 32, v3
	v_and_b32_e32 v0, 24, v0
	v_and_b32_e32 v2, 4, v2
	s_add_i32 m0, s19, 0x10000
	v_or3_b32 v0, v4, v2, v0
	v_add_lshl_u32 v2, v3, v14, 1
	s_waitcnt lgkmcnt(0)
	s_barrier
	global_load_lds_dwordx4 v192, s[24:25]
	s_add_i32 m0, s19, 0x12000
	v_lshl_add_u32 v140, v0, 11, v2
	s_add_u32 s8, s24, 0x40000
	global_load_lds_dwordx4 v140, s[24:25]
	s_addc_u32 s9, s25, 0
	s_add_i32 m0, s19, 0x14000
	v_lshl_add_u32 v138, v1, 11, v2
	global_load_lds_dwordx4 v192, s[8:9]
	s_add_i32 m0, s19, 0x16000
	s_add_u32 s22, s28, s4
	s_addc_u32 s23, s29, s5
	s_add_i32 s21, s19, 0x2000
	global_load_lds_dwordx4 v140, s[8:9]
	s_mov_b32 m0, s19
	s_add_u32 s4, s22, 0x40000
	global_load_lds_dwordx4 v136, s[22:23]
	s_mov_b32 m0, s21
	s_addc_u32 s5, s23, 0
	s_add_i32 s38, s19, 0x4000
	global_load_lds_dwordx4 v138, s[22:23]
	s_mov_b32 m0, s38
	s_add_i32 s39, s19, 0x6000
	global_load_lds_dwordx4 v136, s[4:5]
	s_mov_b32 m0, s39
	s_cmp_eq_u32 s3, 1
	global_load_lds_dwordx4 v138, s[4:5]
	v_mov_b32_e32 v141, v193
	v_mov_b32_e32 v137, v193
	v_mov_b32_e32 v139, v193
	s_cselect_b64 s[4:5], -1, 0
	v_lshl_add_u64 v[6:7], s[24:25], 0, v[192:193]
	v_lshl_add_u64 v[4:5], s[24:25], 0, v[140:141]
	v_lshl_add_u64 v[2:3], s[22:23], 0, v[136:137]
	v_lshl_add_u64 v[0:1], s[22:23], 0, v[138:139]
	s_and_b64 vcc, exec, s[4:5]
	s_cbranch_vccz .LBB0_1265
	s_barrier

;     __device__ bool next(int i, Unit& u) const {
;         const long L = (long)i * G + c; if (L >= nwg) return false;
;         int wgid = (int)L; { const int q = nwg / NXCD, r = nwg % NXCD, xcd = wgid % NXCD, off = wgid / NXCD; wgid = (xcd < r ? xcd * (q + 1) : r * (q + 1) + (xcd - r) * q) + off; }
;         const int nig = WGM * nN, gid = wgid / nig, fm = gid * WGM, gsz = (nM - fm) < WGM ? (nM - fm) : WGM;
;         u.pm = fm + ((wgid % nig) % gsz); u.pn = (wgid % nig) / gsz; return true;
; template <class EpiT, class Sched>
; __device__ __forceinline__ void gemm_phase(LAS unsigned char* lds, const Gemm g, const Sched& S, const EpiT& E, int wv) {
;     ...
;         const bool has_next = S.next(ui + 1, nxt);
;         const char* nA = has_next ? (const char*)g.A + (size_t)nxt.pm * tstepA + (size_t)(nxt.pn >> g.zshift) * g.zA : cA; const char* nB = has_next ? (const char*)g.Bt + (size_t)nxt.pn * tstepB : cB;
.LBB0_1268:
	s_add_i32 s49, s50, 1
	s_mul_i32 s2, s49, s78
	s_mul_hi_u32 s3, s49, s60
	s_add_i32 s3, s3, s2
	s_mul_i32 s2, s49, s60
	s_add_u32 s14, s2, s0
	s_addc_u32 s15, s3, s1
	v_mov_b64_e32 v[0:1], s[36:37]
	v_cmp_ge_i64_e32 vcc, s[14:15], v[0:1]
	v_cmp_lt_i64_e64 s[2:3], s[14:15], v[0:1]
	s_cbranch_vccnz .LBB0_1270
	s_ashr_i32 s10, s14, 31
	s_lshr_b32 s10, s10, 29
	s_add_i32 s10, s14, s10
	s_ashr_i32 s11, s10, 3
	s_and_b32 s10, s10, -8
	s_sub_i32 s10, s14, s10
	s_cmp_lt_i32 s10, 0
	s_cselect_b32 s12, s44, s43
	s_mul_i32 s10, s12, s10
	s_add_i32 s10, s10, s11
	s_ashr_i32 s11, s10, 31
	s_lshr_b32 s11, s11, 25
	s_add_i32 s11, s10, s11
	s_ashr_i32 s12, s11, 7
	s_lshl_b32 s12, s12, 3
	s_sub_i32 s13, s42, s12
	s_min_i32 s13, s13, 8
	s_abs_i32 s14, s13
	v_cvt_f32_u32_e32 v0, s14
	s_sub_i32 s16, 0, s14
	s_and_b32 s11, s11, 0xffffff80
	s_sub_i32 s11, s10, s11
	v_rcp_iflag_f32_e32 v0, v0
	s_abs_i32 s10, s11
	s_xor_b32 s15, s11, s13
	s_ashr_i32 s15, s15, 31
	v_mul_f32_e32 v0, 0x4f7ffffe, v0
	v_cvt_u32_f32_e32 v0, v0
	s_nop 0
	v_readfirstlane_b32 s17, v0
	s_mul_i32 s16, s16, s17
	s_mul_hi_u32 s16, s17, s16
	s_add_i32 s17, s17, s16
	s_mul_hi_u32 s16, s10, s17
	s_mul_i32 s17, s16, s14
	s_sub_i32 s10, s10, s17
	s_add_i32 s26, s16, 1
	s_sub_i32 s17, s10, s14
	s_cmp_ge_u32 s10, s14
	s_cselect_b32 s16, s26, s16
	s_cselect_b32 s10, s17, s10
	s_add_i32 s17, s16, 1
	s_cmp_ge_u32 s10, s14
	s_cselect_b32 s10, s17, s16
	s_xor_b32 s10, s10, s15
	s_sub_i32 s10, s10, s15
	s_mul_i32 s13, s10, s13
	s_sub_i32 s11, s11, s13
	s_add_i32 s12, s11, s12
	s_movk_i32 s14, 0xe0
	s_cmp_eq_u32 s90, 3
	s_cselect_b32 s14, 0x100, s14
	s_mul_i32 s14, s49, s14
	s_add_i32 s14, s79, s14
	s_lshr_b32 s12, s14, 4
	s_and_b32 s10, s14, 15

; #define LAS __attribute__((address_space(3)))
; __device__ __forceinline__ unsigned cvtpk(float lo, float hi) { f32x2 v = {lo, hi}; bf16x2_t b = __builtin_convertvector(v, bf16x2_t); return __builtin_bit_cast(unsigned, b); }
;     __device__ __forceinline__ void operator()(const f32x4 (&acc)[2][2][4][2], const Unit& u, int wr, int wc, int fr, int fq, const LAS float* tab) const {
;     ...
;             if (MODE != 0) {
; #pragma unroll
;                 for (int i = 0; i < 8; ++i) rs[i] = tab[wr * 64 + fr_ + (i >> 2) * HALF + (i & 3) * 16]; }
; #pragma unroll
;             for (int bj = 0; bj < 2; ++bj) {
;                 f32x4 b0 = {0.f, 0.f, 0.f, 0.f}, b1 = b0;
;                 if (MODE != 0) { const LAS float* bp = tab + 256 + wc * 32 + 8 * fq_ + bj * HALF; b0 = *(const LAS f32x4*)bp; b1 = *(const LAS f32x4*)(bp + 4); }
; #pragma unroll
;                 for (int i = 0; i < 8; ++i) { const int ai = i >> 2, m = i & 3; bf16_t* rowp = base + (size_t)(row0 + ai * HALF + m * 16) * ld + c0;
;                     if (MODE == 1 && (u.pn == 4 || u.pn == 5)) {
;                         const bool isx = u.pm < MX / BM; const int bb = isx ? (u.pm >> 3) : (u.pm - MX / BM), ar0 = isx ? CTX + (u.pm & 7) * BM : 0;
;                         rowp = Hout + ((size_t)(bb * 4 + 2 * (u.pn - 4) + bj) * TK + ar0 + wr * 64 + fr_ + ai * HALF + m * 16) * 128 + wc * 32 + 8 * fq_ - bj * HALF; }
;                     f32x4 v0 = acc[ai][bj][m][0], v1 = acc[ai][bj][m][1];
;                     if (MODE != 0) { v0 = v0 * rs[i] + b0; v1 = v1 * rs[i] + b1; }
;                     if (MODE == 4) {
; #pragma unroll
;                         for (int e = 0; e < 4; ++e) { float a = fmaxf(v0[e], 0.f), b = fmaxf(v1[e], 0.f); v0[e] = a * a; v1[e] = b * b; } }
;                     u32x4 w; w.x = cvtpk(v0[0], v0[1]); w.y = cvtpk(v0[2], v0[3]); w.z = cvtpk(v1[0], v1[1]); w.w = cvtpk(v1[2], v1[3]);
;                     *(u32x4*)(rowp + bj * HALF) = w; } }
.LBB0_1274:
	s_lshl_b32 s13, s20, 8
	v_mbcnt_lo_u32_b32 v128, -1, 0
	v_mbcnt_hi_u32_b32 v128, -1, v128
	s_add_i32 s13, s13, s47
	v_and_b32_e32 v129, 15, v128
	s_lshl_b32 s11, s50, 11
	v_or_b32_e32 v156, s13, v129
	v_ashrrev_i32_e32 v128, 1, v128
	s_lshl_b32 s13, s18, 8
	s_add_i32 s11, s11, 0
	v_and_b32_e32 v128, -8, v128
	s_or_b32 s13, s13, s48
	s_add_i32 s11, s11, 0x20400
	s_lshl_b32 s18, s47, 2
	v_add_u32_e32 v154, s13, v128
	s_lshl_b32 s13, s48, 2
	s_add_i32 s18, s11, s18
	s_add_i32 s11, s11, s13
	v_lshl_add_u32 v129, v129, 2, s18
	v_lshl_add_u32 v162, v128, 2, s11
	ds_read2_b32 v[152:153], v129 offset1:16
	ds_read2_b32 v[150:151], v129 offset0:32 offset1:48
	ds_read2_b32 v[148:149], v129 offset0:128 offset1:144
	ds_read2_b32 v[146:147], v129 offset0:160 offset1:176
	ds_read_b128 v[132:135], v162 offset:1024
	ds_read_b128 v[128:131], v162 offset:1040
	v_ashrrev_i32_e32 v155, 31, v154
	v_ashrrev_i32_e32 v157, 31, v156
	v_lshl_add_u64 v[154:155], v[154:155], 1, s[6:7]
	s_waitcnt lgkmcnt(0)
	v_pk_fma_f32 v[124:125], v[124:125], v[152:153], v[132:133] op_sel_hi:[1,0,1]
	v_pk_fma_f32 v[120:121], v[120:121], v[152:153], v[128:129] op_sel_hi:[1,0,1]
	v_pk_fma_f32 v[126:127], v[126:127], v[152:153], v[134:135] op_sel_hi:[1,0,1]
	v_pk_fma_f32 v[122:123], v[122:123], v[152:153], v[130:131] op_sel_hi:[1,0,1]
	v_max_f32_e32 v124, 0, v124
	v_max_f32_e32 v120, 0, v120
	v_max_f32_e32 v125, 0, v125
	v_max_f32_e32 v121, 0, v121
	v_pk_mul_f32 v[124:125], v[124:125], v[124:125]
	v_pk_mul_f32 v[120:121], v[120:121], v[120:121]
	v_max_f32_e32 v126, 0, v126
	v_max_f32_e32 v122, 0, v122
	v_max_f32_e32 v127, 0, v127
	v_max_f32_e32 v123, 0, v123
	v_pk_mul_f32 v[126:127], v[126:127], v[126:127]
	v_pk_mul_f32 v[160:161], v[122:123], v[122:123]
	v_cvt_pk_bf16_f32 v122, v124, v125
	v_cvt_pk_bf16_f32 v124, v120, v121
	v_lshlrev_b64 v[120:121], 13, v[156:157]
	v_cvt_pk_bf16_f32 v123, v126, v127
	v_cvt_pk_bf16_f32 v125, v160, v161
	v_lshl_add_u64 v[120:121], v[154:155], 0, v[120:121]
	global_store_dwordx4 v[120:121], v[122:125], off sc0 sc1
	v_pk_fma_f32 v[108:109], v[108:109], v[150:151], v[132:133] op_sel_hi:[1,0,1]
	v_pk_fma_f32 v[104:105], v[104:105], v[150:151], v[128:129] op_sel_hi:[1,0,1]
	v_mov_b32_e32 v122, v153
	v_pk_fma_f32 v[116:117], v[116:117], v[122:123], v[132:133] op_sel_hi:[1,0,1]
	v_pk_fma_f32 v[112:113], v[112:113], v[122:123], v[128:129] op_sel_hi:[1,0,1]
	v_or_b32_e32 v124, 16, v156
	v_pk_fma_f32 v[118:119], v[118:119], v[122:123], v[134:135] op_sel_hi:[1,0,1]
	v_pk_fma_f32 v[114:115], v[114:115], v[122:123], v[130:131] op_sel_hi:[1,0,1]
	v_max_f32_e32 v116, 0, v116
	v_max_f32_e32 v112, 0, v112
	v_max_f32_e32 v117, 0, v117
	v_max_f32_e32 v113, 0, v113
	v_ashrrev_i32_e32 v125, 31, v124
	v_pk_mul_f32 v[116:117], v[116:117], v[116:117]
	v_pk_mul_f32 v[112:113], v[112:113], v[112:113]
	v_max_f32_e32 v118, 0, v118
	v_max_f32_e32 v114, 0, v114
	v_max_f32_e32 v119, 0, v119
	v_max_f32_e32 v115, 0, v115
	v_pk_mul_f32 v[118:119], v[118:119], v[118:119]
	v_pk_mul_f32 v[126:127], v[114:115], v[114:115]
	v_cvt_pk_bf16_f32 v114, v116, v117
	v_cvt_pk_bf16_f32 v116, v112, v113
	v_lshlrev_b64 v[112:113], 13, v[124:125]
	v_cvt_pk_bf16_f32 v115, v118, v119
	v_cvt_pk_bf16_f32 v117, v126, v127
	v_lshl_add_u64 v[112:113], v[154:155], 0, v[112:113]
	global_store_dwordx4 v[112:113], v[114:117], off sc0 sc1
	v_pk_fma_f32 v[110:111], v[110:111], v[150:151], v[134:135] op_sel_hi:[1,0,1]
	v_pk_fma_f32 v[106:107], v[106:107], v[150:151], v[130:131] op_sel_hi:[1,0,1]
	v_or_b32_e32 v114, 32, v156
	v_max_f32_e32 v108, 0, v108
	v_max_f32_e32 v104, 0, v104
	v_max_f32_e32 v109, 0, v109
	v_max_f32_e32 v105, 0, v105
	v_ashrrev_i32_e32 v115, 31, v114
	v_pk_mul_f32 v[108:109], v[108:109], v[108:109]
	v_pk_mul_f32 v[104:105], v[104:105], v[104:105]
	v_max_f32_e32 v110, 0, v110
	v_max_f32_e32 v106, 0, v106
	v_max_f32_e32 v111, 0, v111
	v_max_f32_e32 v107, 0, v107
	v_pk_mul_f32 v[110:111], v[110:111], v[110:111]
	v_pk_mul_f32 v[116:117], v[106:107], v[106:107]
	v_cvt_pk_bf16_f32 v106, v108, v109
	v_cvt_pk_bf16_f32 v108, v104, v105
	v_lshlrev_b64 v[104:105], 13, v[114:115]
	v_cvt_pk_bf16_f32 v107, v110, v111
	v_cvt_pk_bf16_f32 v109, v116, v117
	v_lshl_add_u64 v[104:105], v[154:155], 0, v[104:105]
	global_store_dwordx4 v[104:105], v[106:109], off sc0 sc1
	v_pk_fma_f32 v[94:95], v[94:95], v[148:149], v[134:135] op_sel_hi:[1,0,1]
	v_pk_fma_f32 v[92:93], v[92:93], v[148:149], v[132:133] op_sel_hi:[1,0,1]
	v_mov_b32_e32 v106, v151
	v_pk_fma_f32 v[100:101], v[100:101], v[106:107], v[132:133] op_sel_hi:[1,0,1]
	v_pk_fma_f32 v[96:97], v[96:97], v[106:107], v[128:129] op_sel_hi:[1,0,1]
	v_or_b32_e32 v108, 48, v156
	v_pk_fma_f32 v[102:103], v[102:103], v[106:107], v[134:135] op_sel_hi:[1,0,1]
	v_pk_fma_f32 v[98:99], v[98:99], v[106:107], v[130:131] op_sel_hi:[1,0,1]
	v_max_f32_e32 v100, 0, v100
	v_max_f32_e32 v96, 0, v96
	v_max_f32_e32 v101, 0, v101
	v_max_f32_e32 v97, 0, v97
	v_ashrrev_i32_e32 v109, 31, v108
	v_pk_mul_f32 v[100:101], v[100:101], v[100:101]
	v_pk_mul_f32 v[96:97], v[96:97], v[96:97]
	v_max_f32_e32 v102, 0, v102
	v_max_f32_e32 v98, 0, v98
	v_max_f32_e32 v103, 0, v103
	v_max_f32_e32 v99, 0, v99
	v_pk_mul_f32 v[102:103], v[102:103], v[102:103]
	v_pk_mul_f32 v[110:111], v[98:99], v[98:99]
	v_cvt_pk_bf16_f32 v98, v100, v101
	v_cvt_pk_bf16_f32 v100, v96, v97
	v_lshlrev_b64 v[96:97], 13, v[108:109]
	v_pk_fma_f32 v[90:91], v[90:91], v[148:149], v[130:131] op_sel_hi:[1,0,1]
	v_pk_fma_f32 v[88:89], v[88:89], v[148:149], v[128:129] op_sel_hi:[1,0,1]
	v_max_f32_e32 v94, 0, v94
	v_max_f32_e32 v95, 0, v95
	v_cvt_pk_bf16_f32 v99, v102, v103
	v_cvt_pk_bf16_f32 v101, v110, v111
; #define LAS __attribute__((address_space(3)))
; __device__ __forceinline__ unsigned cvtpk(float lo, float hi) { f32x2 v = {lo, hi}; bf16x2_t b = __builtin_convertvector(v, bf16x2_t); return __builtin_bit_cast(unsigned, b); }
;     __device__ __forceinline__ void operator()(const f32x4 (&acc)[2][2][4][2], const Unit& u, int wr, int wc, int fr, int fq, const LAS float* tab) const {
;     ...
;             if (MODE != 0) {
; #pragma unroll
;                 for (int i = 0; i < 8; ++i) rs[i] = tab[wr * 64 + fr_ + (i >> 2) * HALF + (i & 3) * 16]; }
; #pragma unroll
;             for (int bj = 0; bj < 2; ++bj) {
;                 f32x4 b0 = {0.f, 0.f, 0.f, 0.f}, b1 = b0;
;                 if (MODE != 0) { const LAS float* bp = tab + 256 + wc * 32 + 8 * fq_ + bj * HALF; b0 = *(const LAS f32x4*)bp; b1 = *(const LAS f32x4*)(bp + 4); }
; #pragma unroll
;                 for (int i = 0; i < 8; ++i) { const int ai = i >> 2, m = i & 3; bf16_t* rowp = base + (size_t)(row0 + ai * HALF + m * 16) * ld + c0;
;                     if (MODE == 1 && (u.pn == 4 || u.pn == 5)) {
;                         const bool isx = u.pm < MX / BM; const int bb = isx ? (u.pm >> 3) : (u.pm - MX / BM), ar0 = isx ? CTX + (u.pm & 7) * BM : 0;
;                         rowp = Hout + ((size_t)(bb * 4 + 2 * (u.pn - 4) + bj) * TK + ar0 + wr * 64 + fr_ + ai * HALF + m * 16) * 128 + wc * 32 + 8 * fq_ - bj * HALF; }
;                     f32x4 v0 = acc[ai][bj][m][0], v1 = acc[ai][bj][m][1];
;                     if (MODE != 0) { v0 = v0 * rs[i] + b0; v1 = v1 * rs[i] + b1; }
;                     if (MODE == 4) {
; #pragma unroll
;                         for (int e = 0; e < 4; ++e) { float a = fmaxf(v0[e], 0.f), b = fmaxf(v1[e], 0.f); v0[e] = a * a; v1[e] = b * b; } }
;                     u32x4 w; w.x = cvtpk(v0[0], v0[1]); w.y = cvtpk(v0[2], v0[3]); w.z = cvtpk(v1[0], v1[1]); w.w = cvtpk(v1[2], v1[3]);
;                     *(u32x4*)(rowp + bj * HALF) = w; } }
	v_lshl_add_u64 v[96:97], v[154:155], 0, v[96:97]
	v_max_f32_e32 v92, 0, v92
	v_max_f32_e32 v88, 0, v88
	v_max_f32_e32 v93, 0, v93
	v_max_f32_e32 v89, 0, v89
	v_max_f32_e32 v90, 0, v90
	v_max_f32_e32 v91, 0, v91
	v_pk_mul_f32 v[94:95], v[94:95], v[94:95]
	s_mov_b32 s11, 0x100000
	global_store_dwordx4 v[96:97], v[98:101], off sc0 sc1
	v_pk_mul_f32 v[92:93], v[92:93], v[92:93]
	v_pk_mul_f32 v[88:89], v[88:89], v[88:89]
	v_pk_mul_f32 v[98:99], v[90:91], v[90:91]
	v_cvt_pk_bf16_f32 v91, v94, v95
	v_add_co_u32_e32 v94, vcc, s11, v120
	v_cvt_pk_bf16_f32 v90, v92, v93
	v_cvt_pk_bf16_f32 v92, v88, v89
	v_cvt_pk_bf16_f32 v93, v98, v99
	v_addc_co_u32_e32 v95, vcc, 0, v121, vcc
	global_store_dwordx4 v[94:95], v[90:93], off sc0 sc1
	v_pk_fma_f32 v[76:77], v[76:77], v[146:147], v[132:133] op_sel_hi:[1,0,1]
	v_pk_fma_f32 v[72:73], v[72:73], v[146:147], v[128:129] op_sel_hi:[1,0,1]
	v_mov_b32_e32 v90, v149
	v_pk_fma_f32 v[84:85], v[84:85], v[90:91], v[132:133] op_sel_hi:[1,0,1]
	v_pk_fma_f32 v[80:81], v[80:81], v[90:91], v[128:129] op_sel_hi:[1,0,1]
	v_add_u32_e32 v92, 0x90, v156
	v_pk_fma_f32 v[86:87], v[86:87], v[90:91], v[134:135] op_sel_hi:[1,0,1]
	v_pk_fma_f32 v[82:83], v[82:83], v[90:91], v[130:131] op_sel_hi:[1,0,1]
	v_max_f32_e32 v84, 0, v84
	v_max_f32_e32 v80, 0, v80
	v_max_f32_e32 v85, 0, v85
	v_max_f32_e32 v81, 0, v81
	v_ashrrev_i32_e32 v93, 31, v92
	v_pk_mul_f32 v[84:85], v[84:85], v[84:85]
	v_pk_mul_f32 v[80:81], v[80:81], v[80:81]
	v_max_f32_e32 v86, 0, v86
	v_max_f32_e32 v82, 0, v82
	v_max_f32_e32 v87, 0, v87
	v_max_f32_e32 v83, 0, v83
	v_pk_mul_f32 v[86:87], v[86:87], v[86:87]
	v_pk_mul_f32 v[94:95], v[82:83], v[82:83]
	v_cvt_pk_bf16_f32 v82, v84, v85
	v_cvt_pk_bf16_f32 v84, v80, v81
	v_lshlrev_b64 v[80:81], 13, v[92:93]
	v_cvt_pk_bf16_f32 v83, v86, v87
	v_cvt_pk_bf16_f32 v85, v94, v95
	v_lshl_add_u64 v[80:81], v[154:155], 0, v[80:81]
	global_store_dwordx4 v[80:81], v[82:85], off sc0 sc1
	v_pk_fma_f32 v[78:79], v[78:79], v[146:147], v[134:135] op_sel_hi:[1,0,1]
	v_pk_fma_f32 v[74:75], v[74:75], v[146:147], v[130:131] op_sel_hi:[1,0,1]
	v_add_u32_e32 v82, 0xa0, v156
	v_max_f32_e32 v76, 0, v76
	v_max_f32_e32 v72, 0, v72
	v_max_f32_e32 v77, 0, v77
	v_max_f32_e32 v73, 0, v73
	v_ashrrev_i32_e32 v83, 31, v82
	v_pk_mul_f32 v[76:77], v[76:77], v[76:77]
	v_pk_mul_f32 v[72:73], v[72:73], v[72:73]
	v_max_f32_e32 v78, 0, v78
	v_max_f32_e32 v74, 0, v74
	v_max_f32_e32 v79, 0, v79
	v_max_f32_e32 v75, 0, v75
	v_pk_mul_f32 v[78:79], v[78:79], v[78:79]
	v_pk_mul_f32 v[84:85], v[74:75], v[74:75]
	v_cvt_pk_bf16_f32 v74, v76, v77
	v_cvt_pk_bf16_f32 v76, v72, v73
	v_lshlrev_b64 v[72:73], 13, v[82:83]
	v_cvt_pk_bf16_f32 v75, v78, v79
	v_cvt_pk_bf16_f32 v77, v84, v85
	v_lshl_add_u64 v[72:73], v[154:155], 0, v[72:73]
	global_store_dwordx4 v[72:73], v[74:77], off sc0 sc1
	s_mov_b64 s[22:23], 0x100000
	v_lshl_add_u64 v[88:89], v[120:121], 0, s[22:23]
	v_mov_b32_e32 v74, v147
	v_pk_fma_f32 v[62:63], v[62:63], v[74:75], v[134:135] op_sel_hi:[1,0,1]
	v_pk_fma_f32 v[60:61], v[60:61], v[74:75], v[132:133] op_sel_hi:[1,0,1]
	v_pk_fma_f32 v[58:59], v[58:59], v[74:75], v[130:131] op_sel_hi:[1,0,1]
	v_pk_fma_f32 v[56:57], v[56:57], v[74:75], v[128:129] op_sel_hi:[1,0,1]
	v_max_f32_e32 v60, 0, v60
	v_max_f32_e32 v56, 0, v56
	v_max_f32_e32 v61, 0, v61
	v_max_f32_e32 v57, 0, v57
	v_max_f32_e32 v62, 0, v62
	v_max_f32_e32 v58, 0, v58
	v_max_f32_e32 v63, 0, v63
	v_max_f32_e32 v59, 0, v59
	v_pk_mul_f32 v[60:61], v[60:61], v[60:61]
	v_pk_mul_f32 v[56:57], v[56:57], v[56:57]
	v_pk_mul_f32 v[62:63], v[62:63], v[62:63]
	v_pk_mul_f32 v[58:59], v[58:59], v[58:59]
	v_cvt_pk_bf16_f32 v82, v60, v61
	v_cvt_pk_bf16_f32 v83, v62, v63
	v_cvt_pk_bf16_f32 v84, v56, v57
	v_cvt_pk_bf16_f32 v85, v58, v59
	ds_read_b128 v[60:63], v162 offset:1536
	ds_read_b128 v[56:59], v162 offset:1552
	v_add_u32_e32 v76, 0xb0, v156
	v_ashrrev_i32_e32 v77, 31, v76
	v_lshlrev_b64 v[76:77], 13, v[76:77]
	s_waitcnt lgkmcnt(0)
	v_pk_fma_f32 v[70:71], v[70:71], v[152:153], v[62:63] op_sel_hi:[1,0,1]
	v_pk_fma_f32 v[64:65], v[64:65], v[152:153], v[56:57] op_sel_hi:[1,0,1]
	v_pk_fma_f32 v[68:69], v[68:69], v[152:153], v[60:61] op_sel_hi:[1,0,1]
	v_pk_fma_f32 v[66:67], v[66:67], v[152:153], v[58:59] op_sel_hi:[1,0,1]
	v_max_f32_e32 v64, 0, v64
	v_max_f32_e32 v65, 0, v65
	v_lshl_add_u64 v[76:77], v[154:155], 0, v[76:77]
	v_max_f32_e32 v68, 0, v68
	v_max_f32_e32 v69, 0, v69
	v_pk_mul_f32 v[78:79], v[64:65], v[64:65]
	v_max_f32_e32 v64, 0, v70
	v_max_f32_e32 v66, 0, v66
	v_max_f32_e32 v65, 0, v71
	v_max_f32_e32 v67, 0, v67
	global_store_dwordx4 v[76:77], v[82:85], off sc0 sc1
	v_pk_mul_f32 v[68:69], v[68:69], v[68:69]
	v_pk_mul_f32 v[70:71], v[64:65], v[64:65]
	v_pk_mul_f32 v[82:83], v[66:67], v[66:67]
	v_pk_fma_f32 v[48:49], v[48:49], v[122:123], v[56:57] op_sel_hi:[1,0,1]
	v_cvt_pk_bf16_f32 v64, v68, v69
	v_cvt_pk_bf16_f32 v65, v70, v71
	v_cvt_pk_bf16_f32 v66, v78, v79
	v_cvt_pk_bf16_f32 v67, v82, v83
	v_pk_fma_f32 v[54:55], v[54:55], v[122:123], v[62:63] op_sel_hi:[1,0,1]
	v_pk_fma_f32 v[52:53], v[52:53], v[122:123], v[60:61] op_sel_hi:[1,0,1]
	v_pk_fma_f32 v[50:51], v[50:51], v[122:123], v[58:59] op_sel_hi:[1,0,1]
	v_max_f32_e32 v48, 0, v48
	v_max_f32_e32 v49, 0, v49
	global_store_dwordx4 v[120:121], v[64:67], off offset:256 sc0 sc1
	v_max_f32_e32 v52, 0, v52
	v_max_f32_e32 v53, 0, v53
	v_pk_mul_f32 v[64:65], v[48:49], v[48:49]
	v_max_f32_e32 v48, 0, v54
	v_max_f32_e32 v50, 0, v50
	v_max_f32_e32 v49, 0, v55
	v_max_f32_e32 v51, 0, v51
	v_pk_mul_f32 v[52:53], v[52:53], v[52:53]
	v_pk_mul_f32 v[54:55], v[48:49], v[48:49]
	v_pk_mul_f32 v[66:67], v[50:51], v[50:51]
	v_pk_fma_f32 v[40:41], v[40:41], v[150:151], v[56:57] op_sel_hi:[1,0,1]
; __device__ __forceinline__ unsigned cvtpk(float lo, float hi) { f32x2 v = {lo, hi}; bf16x2_t b = __builtin_convertvector(v, bf16x2_t); return __builtin_bit_cast(unsigned, b); }
;     __device__ __forceinline__ void operator()(const f32x4 (&acc)[2][2][4][2], const Unit& u, int wr, int wc, int fr, int fq, const LAS float* tab) const {
;     ...
;                 for (int i = 0; i < 8; ++i) { const int ai = i >> 2, m = i & 3; bf16_t* rowp = base + (size_t)(row0 + ai * HALF + m * 16) * ld + c0;
;                     if (MODE == 1 && (u.pn == 4 || u.pn == 5)) {
;                         const bool isx = u.pm < MX / BM; const int bb = isx ? (u.pm >> 3) : (u.pm - MX / BM), ar0 = isx ? CTX + (u.pm & 7) * BM : 0;
;                         rowp = Hout + ((size_t)(bb * 4 + 2 * (u.pn - 4) + bj) * TK + ar0 + wr * 64 + fr_ + ai * HALF + m * 16) * 128 + wc * 32 + 8 * fq_ - bj * HALF; }
;                     f32x4 v0 = acc[ai][bj][m][0], v1 = acc[ai][bj][m][1];
;                     if (MODE != 0) { v0 = v0 * rs[i] + b0; v1 = v1 * rs[i] + b1; }
;                     if (MODE == 4) {
; #pragma unroll
;                         for (int e = 0; e < 4; ++e) { float a = fmaxf(v0[e], 0.f), b = fmaxf(v1[e], 0.f); v0[e] = a * a; v1[e] = b * b; } }
;                     u32x4 w; w.x = cvtpk(v0[0], v0[1]); w.y = cvtpk(v0[2], v0[3]); w.z = cvtpk(v1[0], v1[1]); w.w = cvtpk(v1[2], v1[3]);
;                     *(u32x4*)(rowp + bj * HALF) = w; } }
	v_cvt_pk_bf16_f32 v48, v52, v53
	v_cvt_pk_bf16_f32 v49, v54, v55
	v_cvt_pk_bf16_f32 v50, v64, v65
	v_cvt_pk_bf16_f32 v51, v66, v67
	v_pk_fma_f32 v[46:47], v[46:47], v[150:151], v[62:63] op_sel_hi:[1,0,1]
	v_pk_fma_f32 v[44:45], v[44:45], v[150:151], v[60:61] op_sel_hi:[1,0,1]
	v_pk_fma_f32 v[42:43], v[42:43], v[150:151], v[58:59] op_sel_hi:[1,0,1]
	v_max_f32_e32 v40, 0, v40
	v_max_f32_e32 v41, 0, v41
	global_store_dwordx4 v[112:113], v[48:51], off offset:256 sc0 sc1
	v_max_f32_e32 v44, 0, v44
	v_max_f32_e32 v45, 0, v45
	v_pk_mul_f32 v[48:49], v[40:41], v[40:41]
	v_max_f32_e32 v40, 0, v46
	v_max_f32_e32 v42, 0, v42
	v_max_f32_e32 v41, 0, v47
	v_max_f32_e32 v43, 0, v43
	v_pk_mul_f32 v[44:45], v[44:45], v[44:45]
	v_pk_mul_f32 v[46:47], v[40:41], v[40:41]
	v_pk_mul_f32 v[50:51], v[42:43], v[42:43]
	v_pk_fma_f32 v[32:33], v[32:33], v[106:107], v[56:57] op_sel_hi:[1,0,1]
	v_cvt_pk_bf16_f32 v40, v44, v45
	v_cvt_pk_bf16_f32 v41, v46, v47
	v_cvt_pk_bf16_f32 v42, v48, v49
	v_cvt_pk_bf16_f32 v43, v50, v51
	v_pk_fma_f32 v[38:39], v[38:39], v[106:107], v[62:63] op_sel_hi:[1,0,1]
	v_pk_fma_f32 v[36:37], v[36:37], v[106:107], v[60:61] op_sel_hi:[1,0,1]
	v_pk_fma_f32 v[34:35], v[34:35], v[106:107], v[58:59] op_sel_hi:[1,0,1]
	v_max_f32_e32 v32, 0, v32
	v_max_f32_e32 v33, 0, v33
	global_store_dwordx4 v[104:105], v[40:43], off offset:256 sc0 sc1
	v_max_f32_e32 v36, 0, v36
	v_max_f32_e32 v37, 0, v37
	v_pk_mul_f32 v[40:41], v[32:33], v[32:33]
	v_max_f32_e32 v32, 0, v38
	v_max_f32_e32 v34, 0, v34
	v_max_f32_e32 v33, 0, v39
	v_max_f32_e32 v35, 0, v35
	v_pk_mul_f32 v[36:37], v[36:37], v[36:37]
	v_pk_mul_f32 v[38:39], v[32:33], v[32:33]
	v_pk_mul_f32 v[42:43], v[34:35], v[34:35]
	v_pk_fma_f32 v[24:25], v[24:25], v[148:149], v[56:57] op_sel_hi:[1,0,1]
	v_cvt_pk_bf16_f32 v32, v36, v37
	v_cvt_pk_bf16_f32 v33, v38, v39
	v_cvt_pk_bf16_f32 v34, v40, v41
	v_cvt_pk_bf16_f32 v35, v42, v43
	v_pk_fma_f32 v[30:31], v[30:31], v[148:149], v[62:63] op_sel_hi:[1,0,1]
	v_pk_fma_f32 v[28:29], v[28:29], v[148:149], v[60:61] op_sel_hi:[1,0,1]
	v_pk_fma_f32 v[26:27], v[26:27], v[148:149], v[58:59] op_sel_hi:[1,0,1]
	v_max_f32_e32 v24, 0, v24
	v_max_f32_e32 v25, 0, v25
	global_store_dwordx4 v[96:97], v[32:35], off offset:256 sc0 sc1
	v_max_f32_e32 v28, 0, v28
	v_max_f32_e32 v29, 0, v29
	v_pk_mul_f32 v[32:33], v[24:25], v[24:25]
	v_max_f32_e32 v24, 0, v30
	v_max_f32_e32 v26, 0, v26
	v_max_f32_e32 v25, 0, v31
	v_max_f32_e32 v27, 0, v27
	v_pk_mul_f32 v[28:29], v[28:29], v[28:29]
	v_pk_mul_f32 v[30:31], v[24:25], v[24:25]
	v_pk_mul_f32 v[34:35], v[26:27], v[26:27]
	v_pk_fma_f32 v[16:17], v[16:17], v[90:91], v[56:57] op_sel_hi:[1,0,1]
	v_cvt_pk_bf16_f32 v24, v28, v29
	v_cvt_pk_bf16_f32 v25, v30, v31
	v_cvt_pk_bf16_f32 v26, v32, v33
	v_cvt_pk_bf16_f32 v27, v34, v35
	v_pk_fma_f32 v[22:23], v[22:23], v[90:91], v[62:63] op_sel_hi:[1,0,1]
	v_pk_fma_f32 v[20:21], v[20:21], v[90:91], v[60:61] op_sel_hi:[1,0,1]
	v_pk_fma_f32 v[18:19], v[18:19], v[90:91], v[58:59] op_sel_hi:[1,0,1]
	v_max_f32_e32 v16, 0, v16
	v_max_f32_e32 v17, 0, v17
	global_store_dwordx4 v[88:89], v[24:27], off offset:256 sc0 sc1
	v_max_f32_e32 v20, 0, v20
	v_max_f32_e32 v21, 0, v21
	v_pk_mul_f32 v[24:25], v[16:17], v[16:17]
	v_max_f32_e32 v16, 0, v22
	v_max_f32_e32 v18, 0, v18
	v_max_f32_e32 v17, 0, v23
	v_max_f32_e32 v19, 0, v19
	v_pk_mul_f32 v[20:21], v[20:21], v[20:21]
	v_pk_mul_f32 v[22:23], v[16:17], v[16:17]
	v_pk_mul_f32 v[26:27], v[18:19], v[18:19]
	v_pk_fma_f32 v[8:9], v[8:9], v[146:147], v[56:57] op_sel_hi:[1,0,1]
	v_cvt_pk_bf16_f32 v16, v20, v21
	v_cvt_pk_bf16_f32 v17, v22, v23
	v_cvt_pk_bf16_f32 v18, v24, v25
	v_cvt_pk_bf16_f32 v19, v26, v27
	v_pk_fma_f32 v[14:15], v[14:15], v[146:147], v[62:63] op_sel_hi:[1,0,1]
	v_pk_fma_f32 v[12:13], v[12:13], v[146:147], v[60:61] op_sel_hi:[1,0,1]
	v_pk_fma_f32 v[10:11], v[10:11], v[146:147], v[58:59] op_sel_hi:[1,0,1]
	v_max_f32_e32 v8, 0, v8
	v_max_f32_e32 v9, 0, v9
	global_store_dwordx4 v[80:81], v[16:19], off offset:256 sc0 sc1
	v_max_f32_e32 v12, 0, v12
	v_max_f32_e32 v13, 0, v13
	v_pk_mul_f32 v[16:17], v[8:9], v[8:9]
	v_max_f32_e32 v8, 0, v14
	v_max_f32_e32 v10, 0, v10
	v_max_f32_e32 v9, 0, v15
	v_max_f32_e32 v11, 0, v11
	v_pk_mul_f32 v[12:13], v[12:13], v[12:13]
	v_pk_mul_f32 v[14:15], v[8:9], v[8:9]
	v_pk_mul_f32 v[18:19], v[10:11], v[10:11]
	v_pk_fma_f32 v[0:1], v[0:1], v[74:75], v[56:57] op_sel_hi:[1,0,1]
	v_cvt_pk_bf16_f32 v8, v12, v13
	v_cvt_pk_bf16_f32 v9, v14, v15
	v_cvt_pk_bf16_f32 v10, v16, v17
	v_cvt_pk_bf16_f32 v11, v18, v19
	v_pk_fma_f32 v[6:7], v[6:7], v[74:75], v[62:63] op_sel_hi:[1,0,1]
	v_pk_fma_f32 v[4:5], v[4:5], v[74:75], v[60:61] op_sel_hi:[1,0,1]
	v_pk_fma_f32 v[2:3], v[2:3], v[74:75], v[58:59] op_sel_hi:[1,0,1]
	v_max_f32_e32 v0, 0, v0
	v_max_f32_e32 v1, 0, v1
	global_store_dwordx4 v[72:73], v[8:11], off offset:256 sc0 sc1
	v_max_f32_e32 v4, 0, v4
	v_max_f32_e32 v5, 0, v5
	v_pk_mul_f32 v[8:9], v[0:1], v[0:1]
	v_max_f32_e32 v0, 0, v6
	v_max_f32_e32 v2, 0, v2
	v_max_f32_e32 v1, 0, v7
	v_max_f32_e32 v3, 0, v3
	v_pk_mul_f32 v[4:5], v[4:5], v[4:5]
	v_pk_mul_f32 v[6:7], v[0:1], v[0:1]
	v_pk_mul_f32 v[10:11], v[2:3], v[2:3]
	v_cvt_pk_bf16_f32 v0, v4, v5
	v_cvt_pk_bf16_f32 v1, v6, v7
	v_cvt_pk_bf16_f32 v2, v8, v9
	v_cvt_pk_bf16_f32 v3, v10, v11
	s_andn2_b64 vcc, exec, s[2:3]
	s_mov_b64 s[2:3], -1
	global_store_dwordx4 v[76:77], v[0:3], off offset:256 sc0 sc1
	s_cmp_lg_u32 s50, 0
	s_cbranch_scc1 .Lffn_pub_skip
	s_waitcnt vmcnt(0)
	s_barrier
	s_cmp_lg_u32 s67, 0
	s_cbranch_scc1 .Lffn_pub_skip
	v_readlane_b32 s22, v255, 2
	v_readlane_b32 s23, v255, 3
	s_mov_b64 s[26:27], exec
	s_mov_b64 exec, 1
	s_lshl_b32 s24, s20, 2
	v_mov_b32_e32 v4, s24
	s_nop 4
	global_atomic_add v4, v224, s[22:23]
	s_mov_b64 exec, s[26:27]
.Lffn_pub_skip:
	s_cbranch_vccnz .LBB0_1267
	s_andn2_b64 vcc, exec, s[4:5]
	s_cbranch_vccnz .LBB0_1266
	s_barrier
	s_branch .LBB0_1266

; #define otid() ((wv << 6) | olane())
; #define PG8_WAIT_V(n) asm volatile("s_waitcnt vmcnt(" #n ")" ::: "memory")
; #define PG8_BAR __builtin_amdgcn_s_barrier()
; __device__ __forceinline__ unsigned xb_ld(unsigned* p)              { return __hip_atomic_load(p, __ATOMIC_RELAXED, __HIP_MEMORY_SCOPE_AGENT); }
; __device__ __forceinline__ unsigned xb_add(unsigned* p, unsigned v) { return __hip_atomic_fetch_add(p, v, __ATOMIC_RELAXED, __HIP_MEMORY_SCOPE_AGENT); }
; #define XB_SPIN(cond, bar) do { unsigned _sp = 0; while (cond) { __builtin_amdgcn_s_sleep(1); \
;     if ((++_sp & 255u) == 0u) { if (xb_ld(&(bar)[XB_TMO])) break; if (_sp > XB_SPIN_CAP) { atomicAdd(&(bar)[XB_TMO], 1u); break; } } } } while (0)
; template <class EpiT, class Sched>
; __device__ __forceinline__ void gemm_phase(LAS unsigned char* lds, const Gemm g, const Sched& S, const EpiT& E, int wv) {
;     ...
;     PG8_WAIT_V(0);
;     PG8_BAR;
; __device__ __forceinline__ void xcd_barrier(const XcdBarrier& b, int wv) {
;     asm volatile("s_waitcnt vmcnt(0)" ::: "memory");
;     __syncthreads();
;     if (otid() == 0) {
;         unsigned* bar = b.bar; unsigned bx = b.x;
;         asm volatile("" : "+s"(bar), "+s"(bx));
;         __builtin_amdgcn_s_waitcnt(0);
;         unsigned nloc = b.st[0], nx = b.st[1];
;         if (nloc == 0u) { xcd_barrier_complete(bar, bx, nloc, nx); b.st[0] = nloc; b.st[1] = nx; }
;         const unsigned old = xb_add(&bar[XB_XSUB(bx)], 1u);
;         const unsigned gen = old / nloc;
;         if (old + 1u == (gen + 1u) * nloc) {
;             __builtin_amdgcn_fence(__ATOMIC_RELEASE, "agent");
;             asm volatile("s_waitcnt vmcnt(0)" ::: "memory");
;             const unsigned og = xb_add(&bar[XB_TOP], 1u);
;             const unsigned tg = og / nx;
;             if (og + 1u == (tg + 1u) * nx) xb_add(&bar[XB_TOPGEN], 1u);
;             else XB_SPIN(xb_ld(&bar[XB_TOPGEN]) == tg, bar);
;             __builtin_amdgcn_fence(__ATOMIC_ACQUIRE, "agent");
;             xb_add(&bar[XB_XGEN(bx)], 1u);
;             asm volatile("s_waitcnt vmcnt(0)" ::: "memory");
;         } else {
;             XB_SPIN(xb_ld(&bar[XB_XGEN(bx)]) == gen, bar);
;             __builtin_amdgcn_fence(__ATOMIC_ACQUIRE, "agent");
;             asm volatile("s_waitcnt vmcnt(0)" ::: "memory");
;         }
;     }
;     __syncthreads();
; }
.LBB0_1278:
	s_waitcnt vmcnt(0)
	s_waitcnt vmcnt(0)
	s_barrier
	v_mbcnt_lo_u32_b32 v0, -1, 0
	v_mbcnt_hi_u32_b32 v0, -1, v0
	s_nop 0
	v_or_b32_e32 v0, s67, v0
	v_cmp_eq_u32_e32 vcc, 0, v0
	s_and_saveexec_b64 s[0:1], vcc
	s_xor_b64 s[0:1], exec, s[0:1]
	s_cbranch_execz .LBB0_1323
	v_readlane_b32 s2, v255, 2
	v_readlane_b32 s3, v255, 3
	s_cmp_eq_u32 s90, 3
	s_cselect_b32 s4, 0, 32
	s_cselect_b32 s12, 3, 4
	s_movk_i32 s10, 0xe0
	s_cselect_b32 s10, 0x100, s10
	s_cmp_lt_u32 s79, s4
	s_cbranch_scc1 .Lffn_fp_done
	s_add_i32 s11, s79, s10
.Lffn_fp_loop:
	s_lshr_b32 s13, s11, 4
	s_lshl_b32 s13, s13, 2
	v_mov_b32_e32 v1, s13
	s_add_i32 s11, s11, s10
	s_sub_i32 s12, s12, 1
	global_atomic_add v1, v224, s[2:3]
	s_cmp_lg_u32 s12, 0
	s_cbranch_scc1 .Lffn_fp_loop
.Lffn_fp_done:
	s_cmp_eq_u32 s90, 3
	s_cselect_b32 s4, 0, 32
	s_add_i32 s5, s90, 1
	s_lshl_b32 s5, s5, 4
	s_cmp_lt_u32 s79, s4
	s_cbranch_scc1 .Lffn_w_heavy
	s_sub_i32 s6, s79, s4
	s_lshr_b32 s7, s6, 5
	s_lshl_b32 s7, s7, 3
	s_and_b32 s8, s6, 7
	s_add_i32 s7, s7, s8
	s_lshr_b32 s8, s4, 1
	s_add_i32 s6, s7, s8
	s_mov_b32 s7, s6
	s_branch .Lffn_w_go
.Lffn_w_heavy:
	s_lshr_b32 s6, s79, 2
	s_add_i32 s7, s6, 8
.Lffn_w_go:
	s_lshl_b32 s6, s6, 2
	s_lshl_b32 s7, s7, 2
	v_mov_b32_e32 v1, s6
	v_mov_b32_e32 v2, s7
	s_mov_b32 s8, 0
	s_nop 4
.Lffn_w_spin:
	global_load_dword v3, v1, s[2:3] sc1
	global_load_dword v4, v2, s[2:3] sc1
	s_waitcnt vmcnt(0)
	v_min_u32_e32 v3, v3, v4
	s_nop 1
	v_readfirstlane_b32 s9, v3
	s_nop 3
	s_cmp_ge_u32 s9, s5
	s_cbranch_scc1 .Lffn_w_done
	s_sleep 1
	s_add_i32 s8, s8, 1
	s_cmp_lt_u32 s8, 0xc350
	s_cbranch_scc1 .Lffn_w_spin
.Lffn_w_done:
	s_waitcnt vmcnt(0) lgkmcnt(0)
	buffer_inv sc1
	s_waitcnt vmcnt(0)
.LBB0_1323:
	s_or_b64 exec, exec, s[0:1]
	v_readlane_b32 s0, v255, 0
	v_readlane_b32 s1, v255, 1
	s_waitcnt lgkmcnt(0)
	s_barrier
	s_load_dwordx4 s[8:11], s[0:1], 0xd0
	s_mov_b32 s28, s79
	s_cmp_eq_u32 s90, 3
	s_cselect_b32 s4, 0, 32
	s_cmp_lt_u32 s79, s4
	s_cselect_b32 s5, 0x100, 0
	s_add_i32 s76, s79, 1
	s_add_i32 s76, s76, s5
	s_cmp_lt_i32 s28, s76
	v_mbcnt_lo_u32_b32 v8, -1, 0
	v_mbcnt_hi_u32_b32 v8, -1, v8
	s_cselect_b64 s[0:1], -1, 0
	v_or_b32_e32 v0, s67, v8
	s_and_b64 vcc, exec, s[0:1]
	v_readfirstlane_b32 s2, v0
	s_cbranch_vccnz .LBB0_1326
	s_andn2_b64 vcc, exec, s[0:1]
	s_cbranch_vccz .LBB0_1327

; #define PG8_STAGE(bufoff, gbase, voff) do { _Pragma("unroll") for (int _i = 0; _i < 2; ++_i) \
;         __builtin_amdgcn_global_load_lds((const unsigned*)((const char*)(gbase) + (voff)[_i]), (LAS unsigned*)(lds + (bufoff) + ldsw + _i * 8192), 16, 0, 0); } while (0)
; #define PG8_WAIT_V(n) asm volatile("s_waitcnt vmcnt(" #n ")" ::: "memory")
; #define PG8_BAR __builtin_amdgcn_s_barrier()
;     __device__ bool next(int i, Unit& u) const {
;         const long L = (long)i * G + c; if (L >= nwg) return false;
;         int wgid = (int)L; { const int q = nwg / NXCD, r = nwg % NXCD, xcd = wgid % NXCD, off = wgid / NXCD; wgid = (xcd < r ? xcd * (q + 1) : r * (q + 1) + (xcd - r) * q) + off; }
;         const int nig = WGM * nN, gid = wgid / nig, fm = gid * WGM, gsz = (nM - fm) < WGM ? (nM - fm) : WGM;
;         u.pm = fm + ((wgid % nig) % gsz); u.pn = (wgid % nig) / gsz; return true;
; template <class EpiT, class Sched>
; __device__ __forceinline__ void gemm_phase(LAS unsigned char* lds, const Gemm g, const Sched& S, const EpiT& E, int wv) {
;     ...
;     const char* cA = (const char*)g.A + (size_t)cur.pm * tstepA + (size_t)(cur.pn >> g.zshift) * g.zA; const char* cB = (const char*)g.Bt + (size_t)cur.pn * tstepB;
;     PG8_STAGE(PG8_SB(0, 0), cB, voffB); PG8_STAGE(PG8_SB(0, 1), cB + hstepB, voffB); PG8_STAGE(PG8_SA(0, 0), cA, voffA); PG8_STAGE(PG8_SA(0, 1), cA + hstepA, voffA);
;     if (wr == 1) PG8_BAR;
;     PG8_WAIT_V(2); PG8_BAR;
;     PG8_STAGE(PG8_SB(1, 0), cB + kstep, voffB); PG8_STAGE(PG8_SA(1, 0), cA + kstep, voffA); PG8_STAGE(PG8_SB(1, 1), cB + hstepB + kstep, voffB);
;     PG8_WAIT_V(6); PG8_BAR;
.LBB0_1326:
	s_ashr_i32 s3, s28, 31
	s_lshr_b32 s3, s3, 29
	s_add_i32 s3, s28, s3
	s_ashr_i32 s4, s3, 3
	s_and_b32 s3, s3, -8
	s_sub_i32 s3, s28, s3
	s_cmp_lt_i32 s3, 0
	s_cselect_b32 s5, s46, s45
	s_mul_i32 s3, s3, s5
	s_add_i32 s3, s3, s4
	s_ashr_i32 s4, s3, 31
	s_lshr_b32 s4, s4, 27
	s_add_i32 s4, s3, s4
	s_ashr_i32 s5, s4, 5
	s_lshl_b32 s5, s5, 3
	s_sub_i32 s6, s42, s5
	s_min_i32 s6, s6, 8
	s_abs_i32 s7, s6
	v_cvt_f32_u32_e32 v1, s7
	s_sub_i32 s13, 0, s7
	s_andn2_b32 s4, s4, 31
	s_sub_i32 s3, s3, s4
	v_rcp_iflag_f32_e32 v1, v1
	s_abs_i32 s4, s3
	s_xor_b32 s12, s3, s6
	s_ashr_i32 s12, s12, 31
	v_mul_f32_e32 v1, 0x4f7ffffe, v1
	v_cvt_u32_f32_e32 v1, v1
	s_nop 0
	v_readfirstlane_b32 s14, v1
	s_mul_i32 s13, s13, s14
	s_mul_hi_u32 s13, s14, s13
	s_add_i32 s14, s14, s13
	s_mul_hi_u32 s13, s4, s14
	s_mul_i32 s14, s13, s7
	s_sub_i32 s4, s4, s14
	s_add_i32 s15, s13, 1
	s_sub_i32 s14, s4, s7
	s_cmp_ge_u32 s4, s7
	s_cselect_b32 s13, s15, s13
	s_cselect_b32 s4, s14, s4
	s_add_i32 s14, s13, 1
	s_cmp_ge_u32 s4, s7
	s_cselect_b32 s4, s14, s13
	s_xor_b32 s4, s4, s12
	s_sub_i32 s18, s4, s12
	s_mul_i32 s4, s18, s6
	s_sub_i32 s3, s3, s4
	s_add_i32 s22, s5, s3
	s_cmp_eq_u32 s90, 3
	s_cselect_b32 s5, 0, 32
	s_cmp_lt_u32 s79, s5
	s_cbranch_scc1 .Lffn_m_heavy_a
	s_sub_i32 s3, s79, s5
	s_lshr_b32 s22, s3, 5
	s_lshl_b32 s22, s22, 3
	s_and_b32 s4, s3, 7
	s_add_i32 s22, s22, s4
	s_lshr_b32 s5, s5, 1
	s_add_i32 s22, s22, s5
	s_lshr_b32 s18, s3, 3
	s_and_b32 s18, s18, 3
	s_branch .Lffn_m_done_a
.Lffn_m_heavy_a:
	s_mov_b32 s22, 0
	s_lshr_b32 s4, s79, 2
	s_add_i32 s22, s22, s4
	s_and_b32 s18, s79, 3
.Lffn_m_done_a:
	s_andn2_b64 vcc, exec, s[0:1]
	s_cbranch_vccnz .LBB0_1325
.LBB0_1327:
	v_ashrrev_i32_e32 v2, 31, v0
	v_lshrrev_b32_e32 v2, 26, v2
	v_lshlrev_b32_e32 v1, 4, v0
	v_add_u32_e32 v2, v0, v2
	v_bfe_i32 v0, v0, 27, 1
	v_lshrrev_b32_e32 v0, 22, v0
	v_add_u32_e32 v0, v1, v0
	v_and_b32_e32 v0, 0xfffffc00, v0
	v_sub_u32_e32 v0, v1, v0
	v_ashrrev_i32_e32 v9, 6, v2
	v_lshrrev_b32_e32 v2, 4, v0
	v_bitop3_b32 v0, v2, v0, 32 bitop3:0x6c
	v_ashrrev_i32_e32 v3, 31, v0
	v_lshrrev_b32_e32 v3, 26, v3
	v_add_u32_e32 v3, v0, v3
	v_lshlrev_b32_e32 v2, 3, v9
	v_ashrrev_i32_e32 v10, 6, v3
	v_and_b32_e32 v3, 0xc0, v3
	v_and_b32_e32 v2, -16, v2
	v_sub_u32_e32 v0, v0, v3
	v_add_u32_e32 v2, v10, v2
	v_ashrrev_i16_sdwa v0, v224, sext(v0) dst_sel:DWORD dst_unused:UNUSED_PAD src0_sel:DWORD src1_sel:BYTE_0
	v_lshlrev_b32_e32 v4, 5, v9
	v_bfe_i32 v11, v0, 0, 16
	v_lshlrev_b32_e32 v0, 1, v2
	v_lshrrev_b32_e32 v3, 2, v2
	v_and_b32_e32 v5, 3, v10
	s_mov_b32 s1, 0x7ffe0
	v_and_b32_e32 v4, 32, v4
	v_and_b32_e32 v0, 24, v0
	v_and_b32_e32 v3, 4, v3
	v_and_or_b32 v5, v2, s1, v5
	v_or3_b32 v0, v5, v3, v0
	v_add_lshl_u32 v3, v4, v11, 1
	v_lshl_add_u32 v192, v0, 13, v3
	v_add_u32_e32 v0, 0x2000, v1
	v_ashrrev_i32_e32 v1, 31, v0
	v_lshrrev_b32_e32 v1, 22, v1
	v_add_u32_e32 v1, v0, v1
	v_ashrrev_i32_e32 v12, 10, v1
	v_mul_i32_i24_e32 v1, 0x400, v12
	v_sub_u32_e32 v0, v0, v1
	v_lshrrev_b32_e32 v1, 4, v0
	v_bitop3_b32 v0, v1, v0, 32 bitop3:0x6c
	v_lshl_add_u32 v168, v2, 13, v3
	v_ashrrev_i32_e32 v2, 31, v0
	v_lshrrev_b32_e32 v2, 26, v2
	s_waitcnt lgkmcnt(0)
	s_add_u32 s29, s10, 0x16a00000
	v_lshlrev_b32_e32 v1, 3, v12
	v_add_u32_e32 v2, v0, v2
	s_addc_u32 s30, s11, 0
	v_and_b32_e32 v1, -16, v1
	v_ashrrev_i32_e32 v13, 6, v2
	s_add_u32 s31, s10, 0x2700000
	v_add_u32_e32 v1, v13, v1
	v_and_b32_e32 v4, 3, v13
	s_addc_u32 s36, s11, 0
	v_and_b32_e32 v2, 0xc0, v2
	v_and_or_b32 v4, v1, s1, v4
	s_ashr_i32 s1, s2, 6
	s_ashr_i32 s23, s22, 31
	s_ashr_i32 s19, s18, 31
	s_ashr_i32 s0, s2, 8
	v_sub_u32_e32 v0, v0, v2
	s_lshl_b32 s37, s1, 10
	s_lshl_b64 s[4:5], s[22:23], 21
	s_lshl_b64 s[6:7], s[18:19], 21
	v_ashrrev_i16_sdwa v0, v224, sext(v0) dst_sel:DWORD dst_unused:UNUSED_PAD src0_sel:DWORD src1_sel:BYTE_0
	s_add_u32 s24, s31, s6
	v_lshlrev_b32_e32 v3, 5, v12
	v_bfe_i32 v14, v0, 0, 16
	v_lshlrev_b32_e32 v0, 1, v1
	v_lshrrev_b32_e32 v2, 2, v1
	s_addc_u32 s25, s36, s7
	s_add_i32 s38, s37, 0
	v_and_b32_e32 v3, 32, v3
	v_and_b32_e32 v0, 24, v0
	v_and_b32_e32 v2, 4, v2
	s_add_i32 m0, s38, 0x10000
	v_or3_b32 v0, v4, v2, v0
	v_add_lshl_u32 v2, v3, v14, 1
	global_load_lds_dwordx4 v192, s[24:25]
	s_add_i32 m0, s38, 0x12000
	v_lshl_add_u32 v172, v0, 13, v2
	s_add_u32 s6, s24, 0x100000
	global_load_lds_dwordx4 v172, s[24:25]
	s_addc_u32 s7, s25, 0
	s_add_i32 m0, s38, 0x14000
	v_lshl_add_u32 v170, v1, 13, v2
	global_load_lds_dwordx4 v192, s[6:7]
	s_add_i32 m0, s38, 0x16000
	s_add_u32 s4, s29, s4
	s_addc_u32 s5, s30, s5
	s_add_i32 s39, s38, 0x2000
	global_load_lds_dwordx4 v172, s[6:7]
	s_mov_b32 m0, s38
	s_add_u32 s6, s4, 0x100000
	global_load_lds_dwordx4 v168, s[4:5]
	s_mov_b32 m0, s39
	s_addc_u32 s7, s5, 0
	s_add_i32 s40, s38, 0x4000
	global_load_lds_dwordx4 v170, s[4:5]
	s_mov_b32 m0, s40
	s_add_i32 s41, s38, 0x6000
	global_load_lds_dwordx4 v168, s[6:7]
	s_mov_b32 m0, s41
	v_mov_b32_e32 v173, v193
	global_load_lds_dwordx4 v170, s[6:7]
	v_mov_b32_e32 v169, v193
	v_mov_b32_e32 v171, v193
	s_cmp_eq_u32 s0, 1
	v_lshl_add_u64 v[6:7], s[24:25], 0, v[192:193]
	v_lshl_add_u64 v[4:5], s[24:25], 0, v[172:173]
	v_lshl_add_u64 v[0:1], s[4:5], 0, v[168:169]
	s_cselect_b64 s[6:7], -1, 0
	s_cmp_lg_u32 s0, 1
	v_lshl_add_u64 v[2:3], s[4:5], 0, v[170:171]
	s_cbranch_scc1 .LBB0_1329
	s_barrier

; template <class EpiT, class Sched>
; __device__ __forceinline__ void gemm_phase(LAS unsigned char* lds, const Gemm g, const Sched& S, const EpiT& E, int wv) {
;     ...
;         const bool has_next = S.next(ui + 1, nxt);
;         const char* nA = has_next ? (const char*)g.A + (size_t)nxt.pm * tstepA + (size_t)(nxt.pn >> g.zshift) * g.zA : cA; const char* nB = has_next ? (const char*)g.Bt + (size_t)nxt.pn * tstepB : cB;
;     ...
; #pragma unroll
;         for (int a = 0; a < 2; ++a)
; #pragma unroll
;             for (int b = 0; b < 2; ++b)
; #pragma unroll
;                 for (int m = 0; m < 4; ++m)
; #pragma unroll
;                     for (int n = 0; n < 2; ++n) acc[a][b][m][n] = (f32x4){0.f, 0.f, 0.f, 0.f};
;         cur = nxt; cA = nA; cB = nB; ++ui;
.LBB0_1332:
	s_add_i32 s57, s57, 1
	s_mul_i32 s0, s57, s78
	s_mul_hi_u32 s1, s57, s60
	s_add_i32 s1, s1, s0
	s_mul_i32 s0, s57, s60
	s_add_u32 s0, s0, s28
	s_addc_u32 s1, s1, s54
	v_mov_b64_e32 v[0:1], s[76:77]
	v_cmp_ge_i64_e32 vcc, s[0:1], v[0:1]
	v_cmp_lt_i64_e64 s[2:3], s[0:1], v[0:1]
	s_cbranch_vccnz .LBB0_1334
	s_ashr_i32 s1, s0, 31
	s_lshr_b32 s1, s1, 29
	s_add_i32 s1, s0, s1
	s_ashr_i32 s10, s1, 3
	s_and_b32 s1, s1, -8
	s_sub_i32 s0, s0, s1
	s_lshr_b32 s1, s0, 31
	s_or_b32 s1, s45, s1
	s_mul_i32 s0, s1, s0
	s_add_i32 s0, s0, s10
	s_ashr_i32 s1, s0, 31
	s_lshr_b32 s1, s1, 27
	s_add_i32 s1, s0, s1
	s_ashr_i32 s10, s1, 5
	s_lshl_b32 s11, s10, 3
	s_sub_i32 s10, s42, s11
	s_min_i32 s16, s10, 8
	s_abs_i32 s10, s16
	v_cvt_f32_u32_e32 v0, s10
	s_sub_i32 s19, 0, s10
	s_andn2_b32 s1, s1, 31
	s_sub_i32 s0, s0, s1
	v_rcp_iflag_f32_e32 v0, v0
	s_abs_i32 s1, s0
	s_xor_b32 s17, s0, s16
	s_ashr_i32 s17, s17, 31
	v_mul_f32_e32 v0, 0x4f7ffffe, v0
	v_cvt_u32_f32_e32 v0, v0
	s_nop 0
	v_readfirstlane_b32 s20, v0
	s_mul_i32 s19, s19, s20
	s_mul_hi_u32 s19, s20, s19
	s_add_i32 s20, s20, s19
	s_mul_hi_u32 s19, s1, s20
	s_mul_i32 s20, s19, s10
	s_sub_i32 s1, s1, s20
	s_add_i32 s21, s19, 1
	s_sub_i32 s20, s1, s10
	s_cmp_ge_u32 s1, s10
	s_cselect_b32 s19, s21, s19
	s_cselect_b32 s1, s20, s1
	s_add_i32 s20, s19, 1
	s_cmp_ge_u32 s1, s10
	s_cselect_b32 s1, s20, s19
	s_xor_b32 s1, s1, s17
	s_sub_i32 s10, s1, s17
	s_mul_i32 s1, s10, s16
	s_sub_i32 s0, s0, s1
	s_add_i32 s16, s0, s11
	s_cmp_eq_u32 s90, 3
	s_cselect_b32 s11, 0, 32
	s_cmp_lt_u32 s79, s11
	s_cbranch_scc1 .Lffn_m_heavy_b
	s_sub_i32 s0, s79, s11
	s_lshr_b32 s16, s0, 5
	s_lshl_b32 s16, s16, 3
	s_and_b32 s1, s0, 7
	s_add_i32 s16, s16, s1
	s_lshr_b32 s11, s11, 1
	s_add_i32 s16, s16, s11
	s_lshr_b32 s10, s0, 3
	s_and_b32 s10, s10, 3
	s_branch .Lffn_m_done_b
.Lffn_m_heavy_b:
	s_lshl_b32 s16, s57, 3
	s_lshr_b32 s1, s79, 2
	s_add_i32 s16, s16, s1
	s_and_b32 s10, s79, 3
.Lffn_m_done_b:
.LBB0_1334:
	s_ashr_i32 s17, s16, 31
	s_lshl_b64 s[0:1], s[16:17], 21
	s_add_u32 s0, s29, s0
	s_addc_u32 s1, s30, s1
	s_and_b64 s[20:21], s[2:3], exec
	s_cselect_b32 s17, s1, s5
	s_cselect_b32 s19, s0, s4
	s_ashr_i32 s11, s10, 31
	s_lshl_b64 s[20:21], s[10:11], 21
	s_add_u32 s20, s31, s20
	s_addc_u32 s21, s36, s21
	s_and_b64 s[26:27], s[2:3], exec
	s_cselect_b32 s11, s21, s25
	s_cselect_b32 s23, s20, s24
	s_add_u32 s4, s4, 0x100080
	s_addc_u32 s5, s5, 0
	s_add_u32 s33, s24, 0x100
	v_mov_b32_e32 v0, 0
	s_addc_u32 s58, s25, 0
	s_mov_b32 s59, -2
	v_mov_b32_e32 v1, v0
	v_mov_b32_e32 v2, v0
	v_mov_b32_e32 v3, v0
	v_mov_b32_e32 v4, v0
	v_mov_b32_e32 v5, v0
	v_mov_b32_e32 v6, v0
	v_mov_b32_e32 v7, v0
	v_mov_b32_e32 v8, v0
	v_mov_b32_e32 v9, v0
	v_mov_b32_e32 v10, v0
	v_mov_b32_e32 v11, v0
	v_mov_b32_e32 v12, v0
	v_mov_b32_e32 v13, v0
	v_mov_b32_e32 v14, v0
	v_mov_b32_e32 v15, v0
	v_mov_b32_e32 v16, v0
	v_mov_b32_e32 v17, v0
	v_mov_b32_e32 v18, v0
	v_mov_b32_e32 v19, v0
	v_mov_b32_e32 v20, v0
	v_mov_b32_e32 v21, v0
	v_mov_b32_e32 v22, v0
	v_mov_b32_e32 v23, v0
	v_mov_b32_e32 v24, v0
	v_mov_b32_e32 v25, v0
	v_mov_b32_e32 v26, v0
	v_mov_b32_e32 v27, v0
	v_mov_b32_e32 v28, v0
	v_mov_b32_e32 v29, v0
	v_mov_b32_e32 v30, v0
	v_mov_b32_e32 v31, v0
	v_mov_b32_e32 v64, v0
	v_mov_b32_e32 v65, v0
	v_mov_b32_e32 v66, v0
	v_mov_b32_e32 v67, v0
	v_mov_b32_e32 v68, v0
	v_mov_b32_e32 v69, v0
	v_mov_b32_e32 v70, v0
	v_mov_b32_e32 v71, v0
	v_mov_b32_e32 v72, v0
	v_mov_b32_e32 v73, v0
	v_mov_b32_e32 v74, v0
	v_mov_b32_e32 v75, v0
	v_mov_b32_e32 v76, v0
	v_mov_b32_e32 v77, v0
	v_mov_b32_e32 v78, v0
	v_mov_b32_e32 v79, v0
	v_mov_b32_e32 v80, v0
	v_mov_b32_e32 v81, v0
	v_mov_b32_e32 v82, v0
	v_mov_b32_e32 v83, v0
	v_mov_b32_e32 v84, v0
	v_mov_b32_e32 v85, v0
	v_mov_b32_e32 v86, v0
	v_mov_b32_e32 v87, v0
	v_mov_b32_e32 v88, v0
	v_mov_b32_e32 v89, v0
	v_mov_b32_e32 v90, v0
	v_mov_b32_e32 v91, v0
	v_mov_b32_e32 v92, v0
	v_mov_b32_e32 v93, v0
	v_mov_b32_e32 v94, v0
	v_mov_b32_e32 v95, v0
	v_mov_b32_e32 v32, v0
	v_mov_b32_e32 v33, v0
	v_mov_b32_e32 v34, v0
	v_mov_b32_e32 v35, v0
	v_mov_b32_e32 v36, v0
	v_mov_b32_e32 v37, v0
	v_mov_b32_e32 v38, v0
	v_mov_b32_e32 v39, v0
	v_mov_b32_e32 v40, v0
	v_mov_b32_e32 v41, v0
	v_mov_b32_e32 v42, v0
	v_mov_b32_e32 v43, v0
	v_mov_b32_e32 v44, v0
	v_mov_b32_e32 v45, v0
	v_mov_b32_e32 v46, v0
	v_mov_b32_e32 v47, v0
	v_mov_b32_e32 v48, v0
	v_mov_b32_e32 v49, v0
	v_mov_b32_e32 v50, v0
	v_mov_b32_e32 v51, v0
	v_mov_b32_e32 v52, v0
	v_mov_b32_e32 v53, v0
	v_mov_b32_e32 v54, v0
	v_mov_b32_e32 v55, v0
	v_mov_b32_e32 v56, v0
	v_mov_b32_e32 v57, v0
	v_mov_b32_e32 v58, v0
	v_mov_b32_e32 v59, v0
	v_mov_b32_e32 v60, v0
	v_mov_b32_e32 v61, v0
	v_mov_b32_e32 v62, v0
	v_mov_b32_e32 v63, v0
	v_mov_b32_e32 v96, v0
	v_mov_b32_e32 v97, v0
	v_mov_b32_e32 v98, v0
	v_mov_b32_e32 v99, v0
	v_mov_b32_e32 v100, v0
	v_mov_b32_e32 v101, v0
	v_mov_b32_e32 v102, v0
	v_mov_b32_e32 v103, v0
	v_mov_b32_e32 v104, v0
	v_mov_b32_e32 v105, v0
	v_mov_b32_e32 v106, v0
	v_mov_b32_e32 v107, v0
	v_mov_b32_e32 v108, v0
	v_mov_b32_e32 v109, v0
	v_mov_b32_e32 v110, v0
	v_mov_b32_e32 v111, v0
	v_mov_b32_e32 v112, v0
	v_mov_b32_e32 v113, v0
	v_mov_b32_e32 v114, v0
	v_mov_b32_e32 v115, v0
	v_mov_b32_e32 v116, v0
	v_mov_b32_e32 v117, v0
	v_mov_b32_e32 v118, v0
	v_mov_b32_e32 v119, v0
	v_mov_b32_e32 v120, v0
	v_mov_b32_e32 v121, v0
	v_mov_b32_e32 v122, v0
	v_mov_b32_e32 v123, v0
	v_mov_b32_e32 v124, v0
	v_mov_b32_e32 v125, v0
	v_mov_b32_e32 v126, v0
	v_mov_b32_e32 v127, v0
